# baseline (speedup 1.0000x reference)
; #define NEG_INF (-__builtin_inff())
; DI void softmax_step(float (&sc)[16], AState& st, const KV& kv) {
;   float mx = NEG_INF;
; #pragma unroll
;   for (int i = 0; i < 16; ++i) mx = fmaxf(mx, sc[i]);
;   mx = fmaxf(mx, __shfl_xor(mx, 32));
;   const float mnew = fmaxf(st.m, mx);
;   const float meff = (mnew == NEG_INF) ? 0.f : mnew;
;   const float alpha = __expf(st.m - meff);
;   float rs = 0.f;
; #pragma unroll
;   for (int i = 0; i < 16; ++i) { sc[i] = __expf(sc[i] - meff); rs += sc[i]; }
;   st.l = st.l * alpha + rs;
;   st.m = mnew;
;   if (__any(alpha != 1.f)) {
; #pragma unroll
;     for (int i = 0; i < 16; ++i) { st.o0[i] *= alpha; st.o1[i] *= alpha; }
; DI void band_tile(const KV& kv, const bf16x8 (&q)[4], AState& st, const Fam& f, int n0, int tq, int wtok, float nslope) {
;   const int h2 = (TIDX & 63) >> 5;
;   f32x16 s = qk_tile(kv, q);
;   float sc[16];
;   const int nb = n0 + 8 * h2;
; #pragma unroll
;   for (int i = 0; i < 16; ++i) {
;     const int n = nb + (i & 7) + 16 * (i >> 3);
;     const int stok = n * f.kstride + f.koff;
;     const int dist = tq - stok;
;     const bool valid = (stok >= 0) && (dist >= 0) && (dist <= wtok);
;     sc[i] = valid ? s[i] + nslope * (float)dist : NEG_INF;
;   }
;   softmax_step(sc, st, kv);
; }
.LBB0_788:
	v_mfma_f32_32x32x16_bf16 v[34:49], v[34:37], v[82:85], 0
	v_mov_b32_e32 v0, v159
	s_sub_i32 s14, s49, 32
	v_lshlrev_b32_e32 v0, 2, v0
	s_cmp_gt_i32 s14, -1
	s_cselect_b64 s[46:47], -1, 0
	v_mfma_f32_32x32x16_bf16 v[34:49], v[114:117], v[86:89], v[34:49]
	v_add_u32_e32 v114, s11, v133
	v_and_b32_e32 v115, 0x80, v0
	v_sub_u32_e32 v0, v114, v115
	v_mfma_f32_32x32x16_bf16 v[34:49], v[118:121], v[90:93], v[34:49]
	v_mfma_f32_32x32x16_bf16 v[34:49], v[122:125], v[94:97], v[34:49]
	s_nop 11
	v_mov_b32_e32 v196, v0
	v_add_u32_e32 v197, -16, v0
	v_cmp_gt_u32_e32 vcc, s8, v196
	v_cmp_gt_u32_e64 s[46:47], s8, v197
	v_cvt_f32_i32_e32 v196, v196
	v_cvt_f32_i32_e32 v197, v197
	v_fma_f32 v34, -v189, v196, v34
	v_fma_f32 v35, -v189, v197, v35
	v_cndmask_b32_e32 v34, v184, v34, vcc
	v_cndmask_b32_e64 v35, v184, v35, s[46:47]
	v_add_u32_e32 v196, 0xffffffe0, v0
	v_add_u32_e32 v197, 0xffffffd0, v0
	v_cmp_gt_u32_e32 vcc, s8, v196
	v_cmp_gt_u32_e64 s[46:47], s8, v197
	v_cvt_f32_i32_e32 v196, v196
	v_cvt_f32_i32_e32 v197, v197
	v_fma_f32 v36, -v189, v196, v36
	v_fma_f32 v37, -v189, v197, v37
	v_cndmask_b32_e32 v36, v184, v36, vcc
	v_cndmask_b32_e64 v37, v184, v37, s[46:47]
	v_add_u32_e32 v196, 0xffffffc0, v0
	v_add_u32_e32 v197, 0xffffffb0, v0
	v_cmp_gt_u32_e32 vcc, s8, v196
	v_cmp_gt_u32_e64 s[46:47], s8, v197
	v_cvt_f32_i32_e32 v196, v196
	v_cvt_f32_i32_e32 v197, v197
	v_fma_f32 v38, -v189, v196, v38
	v_fma_f32 v39, -v189, v197, v39
	v_cndmask_b32_e32 v38, v184, v38, vcc
	v_cndmask_b32_e64 v39, v184, v39, s[46:47]
	v_add_u32_e32 v196, 0xffffffa0, v0
	v_add_u32_e32 v197, 0xffffff90, v0
	v_cmp_gt_u32_e32 vcc, s8, v196
	v_cmp_gt_u32_e64 s[46:47], s8, v197
	v_cvt_f32_i32_e32 v196, v196
	v_cvt_f32_i32_e32 v197, v197
	v_fma_f32 v40, -v189, v196, v40
	v_fma_f32 v41, -v189, v197, v41
	v_cndmask_b32_e32 v40, v184, v40, vcc
	v_cndmask_b32_e64 v41, v184, v41, s[46:47]
	v_add_u32_e32 v196, 0xffffff00, v0
	v_add_u32_e32 v197, 0xfffffef0, v0
	v_cmp_gt_u32_e32 vcc, s8, v196
	v_cmp_gt_u32_e64 s[46:47], s8, v197
	v_cvt_f32_i32_e32 v196, v196
	v_cvt_f32_i32_e32 v197, v197
	v_fma_f32 v42, -v189, v196, v42
	v_fma_f32 v43, -v189, v197, v43
	v_cndmask_b32_e32 v42, v184, v42, vcc
	v_cndmask_b32_e64 v43, v184, v43, s[46:47]
	v_add_u32_e32 v196, 0xfffffee0, v0
	v_add_u32_e32 v197, 0xfffffed0, v0
	v_cmp_gt_u32_e32 vcc, s8, v196
	v_cmp_gt_u32_e64 s[46:47], s8, v197
	v_cvt_f32_i32_e32 v196, v196
	v_cvt_f32_i32_e32 v197, v197
	v_fma_f32 v44, -v189, v196, v44
	v_fma_f32 v45, -v189, v197, v45
	v_cndmask_b32_e32 v44, v184, v44, vcc
	v_cndmask_b32_e64 v45, v184, v45, s[46:47]
	v_add_u32_e32 v196, 0xfffffec0, v0
	v_add_u32_e32 v197, 0xfffffeb0, v0
	v_cmp_gt_u32_e32 vcc, s8, v196
	v_cmp_gt_u32_e64 s[46:47], s8, v197
	v_cvt_f32_i32_e32 v196, v196
	v_cvt_f32_i32_e32 v197, v197
	v_fma_f32 v46, -v189, v196, v46
	v_fma_f32 v47, -v189, v197, v47
	v_cndmask_b32_e32 v46, v184, v46, vcc
	v_cndmask_b32_e64 v47, v184, v47, s[46:47]
	v_add_u32_e32 v196, 0xfffffea0, v0
	v_add_u32_e32 v197, 0xfffffe90, v0
	v_cmp_gt_u32_e32 vcc, s8, v196
	v_cmp_gt_u32_e64 s[46:47], s8, v197
	v_cvt_f32_i32_e32 v196, v196
	v_cvt_f32_i32_e32 v197, v197
	v_fma_f32 v48, -v189, v196, v48
	v_fma_f32 v49, -v189, v197, v49
	v_cndmask_b32_e32 v48, v184, v48, vcc
	v_cndmask_b32_e64 v49, v184, v49, s[46:47]
	v_max3_f32 v0, v34, s35, v35
	v_max3_f32 v0, v0, v36, v37
	v_max3_f32 v0, v0, v38, v39
	v_mbcnt_hi_u32_b32 v114, -1, v180
	v_max3_f32 v0, v0, v40, v41
	v_and_b32_e32 v116, 64, v114
	v_max3_f32 v0, v0, v42, v43
	v_xor_b32_e32 v115, 32, v114
	v_add_u32_e32 v116, 64, v116
	v_max3_f32 v0, v0, v44, v45
	v_cmp_lt_i32_e32 vcc, v115, v116
	v_max3_f32 v0, v0, v46, v47
	v_max3_f32 v0, v0, v48, v49
	v_cndmask_b32_e32 v114, v114, v115, vcc
	v_mov_b32_e32 v114, v0
	s_nop 1
	v_permlane32_swap_b32_e32 v114, v0
	v_max3_f32 v131, v135, v0, v114
	v_cmp_neq_f32_e32 vcc, s35, v131
	s_nop 1
	v_cndmask_b32_e32 v114, 0, v131, vcc
	v_sub_f32_e32 v0, v135, v114
	v_mul_f32_e32 v0, 0x3fb8aa3b, v0
	v_exp_f32_e32 v0, v0
	s_nop 0
	v_cmp_neq_f32_e32 vcc, 1.0, v0
	s_cbranch_vccz .LBB0_790
	v_pk_mul_f32 v[32:33], v[32:33], v[0:1] op_sel_hi:[1,0]
	v_pk_mul_f32 v[30:31], v[30:31], v[0:1] op_sel_hi:[1,0]
	v_pk_mul_f32 v[28:29], v[28:29], v[0:1] op_sel_hi:[1,0]
	v_pk_mul_f32 v[26:27], v[26:27], v[0:1] op_sel_hi:[1,0]
	v_pk_mul_f32 v[24:25], v[24:25], v[0:1] op_sel_hi:[1,0]
	v_pk_mul_f32 v[22:23], v[22:23], v[0:1] op_sel_hi:[1,0]
	v_pk_mul_f32 v[20:21], v[20:21], v[0:1] op_sel_hi:[1,0]
	v_pk_mul_f32 v[18:19], v[18:19], v[0:1] op_sel_hi:[1,0]
	v_pk_mul_f32 v[16:17], v[16:17], v[0:1] op_sel_hi:[1,0]
	v_pk_mul_f32 v[14:15], v[14:15], v[0:1] op_sel_hi:[1,0]
	v_pk_mul_f32 v[12:13], v[12:13], v[0:1] op_sel_hi:[1,0]
	v_pk_mul_f32 v[10:11], v[10:11], v[0:1] op_sel_hi:[1,0]
	v_pk_mul_f32 v[8:9], v[8:9], v[0:1] op_sel_hi:[1,0]
	v_pk_mul_f32 v[6:7], v[6:7], v[0:1] op_sel_hi:[1,0]
	v_pk_mul_f32 v[4:5], v[4:5], v[0:1] op_sel_hi:[1,0]
	v_pk_mul_f32 v[2:3], v[2:3], v[0:1] op_sel_hi:[1,0]

; #define NEG_INF (-__builtin_inff())
; DI void softmax_step(float (&sc)[16], AState& st, const KV& kv) {
;   float mx = NEG_INF;
; #pragma unroll
;   for (int i = 0; i < 16; ++i) mx = fmaxf(mx, sc[i]);
;   mx = fmaxf(mx, __shfl_xor(mx, 32));
;   const float mnew = fmaxf(st.m, mx);
;   const float meff = (mnew == NEG_INF) ? 0.f : mnew;
;   const float alpha = __expf(st.m - meff);
;   float rs = 0.f;
; #pragma unroll
;   for (int i = 0; i < 16; ++i) { sc[i] = __expf(sc[i] - meff); rs += sc[i]; }
;   st.l = st.l * alpha + rs;
;   st.m = mnew;
;   if (__any(alpha != 1.f)) {
; #pragma unroll
;     for (int i = 0; i < 16; ++i) { st.o0[i] *= alpha; st.o1[i] *= alpha; }
; DI void band_tile(const KV& kv, const bf16x8 (&q)[4], AState& st, const Fam& f, int n0, int tq, int wtok, float nslope) {
;   const int h2 = (TIDX & 63) >> 5;
;   f32x16 s = qk_tile(kv, q);
;   float sc[16];
;   const int nb = n0 + 8 * h2;
; #pragma unroll
;   for (int i = 0; i < 16; ++i) {
;     const int n = nb + (i & 7) + 16 * (i >> 3);
;     const int stok = n * f.kstride + f.koff;
;     const int dist = tq - stok;
;     const bool valid = (stok >= 0) && (dist >= 0) && (dist <= wtok);
;     sc[i] = valid ? s[i] + nslope * (float)dist : NEG_INF;
;   }
;   softmax_step(sc, st, kv);
; }
.LBB0_796:
	v_mfma_f32_32x32x16_bf16 v[34:49], v[34:37], v[82:85], 0
	v_mov_b32_e32 v0, v159
	s_sub_i32 s14, s10, 32
	s_cmp_gt_i32 s14, -1
	s_cselect_b64 s[46:47], -1, 0
	v_mfma_f32_32x32x16_bf16 v[34:49], v[114:117], v[86:89], v[34:49]
	v_and_b32_e32 v114, 32, v0
	v_add_u32_e32 v0, s23, v133
	v_sub_u32_e32 v0, v0, v114
	v_mfma_f32_32x32x16_bf16 v[34:49], v[118:121], v[90:93], v[34:49]
	v_mfma_f32_32x32x16_bf16 v[34:49], v[122:125], v[94:97], v[34:49]
	s_nop 11
	v_mov_b32_e32 v196, v0
	v_add_u32_e32 v197, -4, v0
	v_cmp_gt_u32_e32 vcc, s34, v196
	v_cmp_gt_u32_e64 s[46:47], s34, v197
	v_cvt_f32_i32_e32 v196, v196
	v_cvt_f32_i32_e32 v197, v197
	v_fma_f32 v34, -v189, v196, v34
	v_fma_f32 v35, -v189, v197, v35
	v_cndmask_b32_e32 v34, v184, v34, vcc
	v_cndmask_b32_e64 v35, v184, v35, s[46:47]
	v_add_u32_e32 v196, -8, v0
	v_add_u32_e32 v197, -12, v0
	v_cmp_gt_u32_e32 vcc, s34, v196
	v_cmp_gt_u32_e64 s[46:47], s34, v197
	v_cvt_f32_i32_e32 v196, v196
	v_cvt_f32_i32_e32 v197, v197
	v_fma_f32 v36, -v189, v196, v36
	v_fma_f32 v37, -v189, v197, v37
	v_cndmask_b32_e32 v36, v184, v36, vcc
	v_cndmask_b32_e64 v37, v184, v37, s[46:47]
	v_add_u32_e32 v196, -16, v0
	v_add_u32_e32 v197, 0xffffffec, v0
	v_cmp_gt_u32_e32 vcc, s34, v196
	v_cmp_gt_u32_e64 s[46:47], s34, v197
	v_cvt_f32_i32_e32 v196, v196
	v_cvt_f32_i32_e32 v197, v197
	v_fma_f32 v38, -v189, v196, v38
	v_fma_f32 v39, -v189, v197, v39
	v_cndmask_b32_e32 v38, v184, v38, vcc
	v_cndmask_b32_e64 v39, v184, v39, s[46:47]
	v_add_u32_e32 v196, 0xffffffe8, v0
	v_add_u32_e32 v197, 0xffffffe4, v0
	v_cmp_gt_u32_e32 vcc, s34, v196
	v_cmp_gt_u32_e64 s[46:47], s34, v197
	v_cvt_f32_i32_e32 v196, v196
	v_cvt_f32_i32_e32 v197, v197
	v_fma_f32 v40, -v189, v196, v40
	v_fma_f32 v41, -v189, v197, v41
	v_cndmask_b32_e32 v40, v184, v40, vcc
	v_cndmask_b32_e64 v41, v184, v41, s[46:47]
	v_add_u32_e32 v196, 0xffffffc0, v0
	v_add_u32_e32 v197, 0xffffffbc, v0
	v_cmp_gt_u32_e32 vcc, s34, v196
	v_cmp_gt_u32_e64 s[46:47], s34, v197
	v_cvt_f32_i32_e32 v196, v196
	v_cvt_f32_i32_e32 v197, v197
	v_fma_f32 v42, -v189, v196, v42
	v_fma_f32 v43, -v189, v197, v43
	v_cndmask_b32_e32 v42, v184, v42, vcc
	v_cndmask_b32_e64 v43, v184, v43, s[46:47]
	v_add_u32_e32 v196, 0xffffffb8, v0
	v_add_u32_e32 v197, 0xffffffb4, v0
	v_cmp_gt_u32_e32 vcc, s34, v196
	v_cmp_gt_u32_e64 s[46:47], s34, v197
	v_cvt_f32_i32_e32 v196, v196
	v_cvt_f32_i32_e32 v197, v197
	v_fma_f32 v44, -v189, v196, v44
	v_fma_f32 v45, -v189, v197, v45
	v_cndmask_b32_e32 v44, v184, v44, vcc
	v_cndmask_b32_e64 v45, v184, v45, s[46:47]
	v_add_u32_e32 v196, 0xffffffb0, v0
	v_add_u32_e32 v197, 0xffffffac, v0
	v_cmp_gt_u32_e32 vcc, s34, v196
	v_cmp_gt_u32_e64 s[46:47], s34, v197
	v_cvt_f32_i32_e32 v196, v196
	v_cvt_f32_i32_e32 v197, v197
	v_fma_f32 v46, -v189, v196, v46
	v_fma_f32 v47, -v189, v197, v47
	v_cndmask_b32_e32 v46, v184, v46, vcc
	v_cndmask_b32_e64 v47, v184, v47, s[46:47]
	v_add_u32_e32 v196, 0xffffffa8, v0
	v_add_u32_e32 v197, 0xffffffa4, v0
	v_cmp_gt_u32_e32 vcc, s34, v196
	v_cmp_gt_u32_e64 s[46:47], s34, v197
	v_cvt_f32_i32_e32 v196, v196
	v_cvt_f32_i32_e32 v197, v197
	v_fma_f32 v48, -v189, v196, v48
	v_fma_f32 v49, -v189, v197, v49
	v_cndmask_b32_e32 v48, v184, v48, vcc
	v_cndmask_b32_e64 v49, v184, v49, s[46:47]
	v_max3_f32 v0, v34, s35, v35
	v_max3_f32 v0, v0, v36, v37
	v_max3_f32 v0, v0, v38, v39
	v_mbcnt_hi_u32_b32 v114, -1, v180
	v_max3_f32 v0, v0, v40, v41
	v_and_b32_e32 v116, 64, v114
	v_max3_f32 v0, v0, v42, v43
	v_xor_b32_e32 v115, 32, v114
	v_add_u32_e32 v116, 64, v116
	v_max3_f32 v0, v0, v44, v45
	v_cmp_lt_i32_e32 vcc, v115, v116
	v_max3_f32 v0, v0, v46, v47
	v_max3_f32 v0, v0, v48, v49
	v_cndmask_b32_e32 v114, v114, v115, vcc
	v_mov_b32_e32 v114, v0
	s_nop 1
	v_permlane32_swap_b32_e32 v114, v0
	v_max3_f32 v191, v131, v0, v114
	v_cmp_neq_f32_e32 vcc, s35, v191
	s_nop 1
	v_cndmask_b32_e32 v114, 0, v191, vcc
	v_sub_f32_e32 v0, v131, v114
	v_mul_f32_e32 v0, 0x3fb8aa3b, v0
	v_exp_f32_e32 v0, v0
	s_nop 0
	v_cmp_neq_f32_e32 vcc, 1.0, v0
	s_cbranch_vccz .LBB0_798
	v_pk_mul_f32 v[32:33], v[32:33], v[0:1] op_sel_hi:[1,0]
	v_pk_mul_f32 v[30:31], v[30:31], v[0:1] op_sel_hi:[1,0]
	v_pk_mul_f32 v[28:29], v[28:29], v[0:1] op_sel_hi:[1,0]
	v_pk_mul_f32 v[26:27], v[26:27], v[0:1] op_sel_hi:[1,0]
	v_pk_mul_f32 v[24:25], v[24:25], v[0:1] op_sel_hi:[1,0]
	v_pk_mul_f32 v[22:23], v[22:23], v[0:1] op_sel_hi:[1,0]
	v_pk_mul_f32 v[20:21], v[20:21], v[0:1] op_sel_hi:[1,0]
	v_pk_mul_f32 v[18:19], v[18:19], v[0:1] op_sel_hi:[1,0]
	v_pk_mul_f32 v[16:17], v[16:17], v[0:1] op_sel_hi:[1,0]
	v_pk_mul_f32 v[14:15], v[14:15], v[0:1] op_sel_hi:[1,0]
	v_pk_mul_f32 v[12:13], v[12:13], v[0:1] op_sel_hi:[1,0]
	v_pk_mul_f32 v[10:11], v[10:11], v[0:1] op_sel_hi:[1,0]
	v_pk_mul_f32 v[8:9], v[8:9], v[0:1] op_sel_hi:[1,0]
	v_pk_mul_f32 v[6:7], v[6:7], v[0:1] op_sel_hi:[1,0]
	v_pk_mul_f32 v[4:5], v[4:5], v[0:1] op_sel_hi:[1,0]
	v_pk_mul_f32 v[2:3], v[2:3], v[0:1] op_sel_hi:[1,0]

; #define NEG_INF (-__builtin_inff())
; DI void softmax_step(float (&sc)[16], AState& st, const KV& kv) {
;   float mx = NEG_INF;
; #pragma unroll
;   for (int i = 0; i < 16; ++i) mx = fmaxf(mx, sc[i]);
;   mx = fmaxf(mx, __shfl_xor(mx, 32));
;   const float mnew = fmaxf(st.m, mx);
;   const float meff = (mnew == NEG_INF) ? 0.f : mnew;
;   const float alpha = __expf(st.m - meff);
;   float rs = 0.f;
; #pragma unroll
;   for (int i = 0; i < 16; ++i) { sc[i] = __expf(sc[i] - meff); rs += sc[i]; }
;   st.l = st.l * alpha + rs;
;   st.m = mnew;
;   if (__any(alpha != 1.f)) {
; #pragma unroll
;     for (int i = 0; i < 16; ++i) { st.o0[i] *= alpha; st.o1[i] *= alpha; }
; DI void band_tile(const KV& kv, const bf16x8 (&q)[4], AState& st, const Fam& f, int n0, int tq, int wtok, float nslope) {
;   const int h2 = (TIDX & 63) >> 5;
;   f32x16 s = qk_tile(kv, q);
;   float sc[16];
;   const int nb = n0 + 8 * h2;
; #pragma unroll
;   for (int i = 0; i < 16; ++i) {
;     const int n = nb + (i & 7) + 16 * (i >> 3);
;     const int stok = n * f.kstride + f.koff;
;     const int dist = tq - stok;
;     const bool valid = (stok >= 0) && (dist >= 0) && (dist <= wtok);
;     sc[i] = valid ? s[i] + nslope * (float)dist : NEG_INF;
;   }
;   softmax_step(sc, st, kv);
; }
.LBB0_804:
	v_mfma_f32_32x32x16_bf16 v[66:81], v[66:69], v[82:85], 0
	v_mov_b32_e32 v0, v159
	s_cmp_gt_i32 s10, -1
	v_lshrrev_b32_e32 v0, 2, v0
	s_cselect_b64 s[46:47], -1, 0
	s_movk_i32 s14, 0xffef
	v_mfma_f32_32x32x16_bf16 v[66:81], v[146:149], v[86:89], v[66:81]
	v_and_b32_e32 v146, 8, v0
	v_add_u32_e32 v147, s12, v192
	v_sub_u32_e32 v146, v147, v146
	v_mfma_f32_32x32x16_bf16 v[66:81], v[150:153], v[90:93], v[66:81]
	v_mfma_f32_32x32x16_bf16 v[66:81], v[154:157], v[94:97], v[66:81]
	s_nop 11
	v_mov_b32_e32 v196, v146
	v_add_u32_e32 v197, -1, v146
	v_cmp_gt_u32_e32 vcc, s9, v196
	v_cmp_gt_u32_e64 s[46:47], s9, v197
	v_cvt_f32_i32_e32 v196, v196
	v_cvt_f32_i32_e32 v197, v197
	v_fma_f32 v66, -v189, v196, v66
	v_fma_f32 v67, -v189, v197, v67
	v_cndmask_b32_e32 v66, v184, v66, vcc
	v_cndmask_b32_e64 v67, v184, v67, s[46:47]
	v_add_u32_e32 v196, -2, v146
	v_add_u32_e32 v197, -3, v146
	v_cmp_gt_u32_e32 vcc, s9, v196
	v_cmp_gt_u32_e64 s[46:47], s9, v197
	v_cvt_f32_i32_e32 v196, v196
	v_cvt_f32_i32_e32 v197, v197
	v_fma_f32 v68, -v189, v196, v68
	v_fma_f32 v69, -v189, v197, v69
	v_cndmask_b32_e32 v68, v184, v68, vcc
	v_cndmask_b32_e64 v69, v184, v69, s[46:47]
	v_add_u32_e32 v196, -4, v146
	v_add_u32_e32 v197, -5, v146
	v_cmp_gt_u32_e32 vcc, s9, v196
	v_cmp_gt_u32_e64 s[46:47], s9, v197
	v_cvt_f32_i32_e32 v196, v196
	v_cvt_f32_i32_e32 v197, v197
	v_fma_f32 v70, -v189, v196, v70
	v_fma_f32 v71, -v189, v197, v71
	v_cndmask_b32_e32 v70, v184, v70, vcc
	v_cndmask_b32_e64 v71, v184, v71, s[46:47]
	v_add_u32_e32 v196, -6, v146
	v_add_u32_e32 v197, -7, v146
	v_cmp_gt_u32_e32 vcc, s9, v196
	v_cmp_gt_u32_e64 s[46:47], s9, v197
	v_cvt_f32_i32_e32 v196, v196
	v_cvt_f32_i32_e32 v197, v197
	v_fma_f32 v72, -v189, v196, v72
	v_fma_f32 v73, -v189, v197, v73
	v_cndmask_b32_e32 v72, v184, v72, vcc
	v_cndmask_b32_e64 v73, v184, v73, s[46:47]
	v_add_u32_e32 v196, -16, v146
	v_add_u32_e32 v197, 0xffffffef, v146
	v_cmp_gt_u32_e32 vcc, s9, v196
	v_cmp_gt_u32_e64 s[46:47], s9, v197
	v_cvt_f32_i32_e32 v196, v196
	v_cvt_f32_i32_e32 v197, v197
	v_fma_f32 v74, -v189, v196, v74
	v_fma_f32 v75, -v189, v197, v75
	v_cndmask_b32_e32 v74, v184, v74, vcc
	v_cndmask_b32_e64 v75, v184, v75, s[46:47]
	v_add_u32_e32 v196, 0xffffffee, v146
	v_add_u32_e32 v197, 0xffffffed, v146
	v_cmp_gt_u32_e32 vcc, s9, v196
	v_cmp_gt_u32_e64 s[46:47], s9, v197
	v_cvt_f32_i32_e32 v196, v196
	v_cvt_f32_i32_e32 v197, v197
	v_fma_f32 v76, -v189, v196, v76
	v_fma_f32 v77, -v189, v197, v77
	v_cndmask_b32_e32 v76, v184, v76, vcc
	v_cndmask_b32_e64 v77, v184, v77, s[46:47]
	v_add_u32_e32 v196, 0xffffffec, v146
	v_add_u32_e32 v197, 0xffffffeb, v146
	v_cmp_gt_u32_e32 vcc, s9, v196
	v_cmp_gt_u32_e64 s[46:47], s9, v197
	v_cvt_f32_i32_e32 v196, v196
	v_cvt_f32_i32_e32 v197, v197
	v_fma_f32 v78, -v189, v196, v78
	v_fma_f32 v147, -v189, v197, v79
	v_cndmask_b32_e32 v78, v184, v78, vcc
	v_cndmask_b32_e64 v147, v184, v147, s[46:47]
	v_add_u32_e32 v196, 0xffffffea, v146
	v_add_u32_e32 v197, 0xffffffe9, v146
	v_cmp_gt_u32_e32 vcc, s9, v196
	v_cmp_gt_u32_e64 s[46:47], s9, v197
	v_cvt_f32_i32_e32 v196, v196
	v_cvt_f32_i32_e32 v197, v197
	v_fma_f32 v148, -v189, v196, v80
	v_fma_f32 v149, -v189, v197, v81
	v_cndmask_b32_e32 v148, v184, v148, vcc
	v_cndmask_b32_e64 v149, v184, v149, s[46:47]
	v_mbcnt_hi_u32_b32 v79, -1, v180
	v_max3_f32 v0, v66, s35, v67
	v_max3_f32 v0, v0, v68, v69
	v_max3_f32 v0, v0, v70, v71
	v_max3_f32 v0, v0, v72, v73
	v_and_b32_e32 v81, 64, v79
	v_max3_f32 v0, v0, v74, v75
	v_xor_b32_e32 v80, 32, v79
	v_add_u32_e32 v81, 64, v81
	v_max3_f32 v0, v0, v76, v77
	v_cmp_lt_i32_e32 vcc, v80, v81
	v_max3_f32 v0, v0, v78, v147
	v_max3_f32 v0, v0, v148, v149
	v_cndmask_b32_e32 v146, v79, v80, vcc
	v_mov_b32_e32 v146, v0
	s_nop 1
	v_permlane32_swap_b32_e32 v146, v0
	v_max3_f32 v146, v191, v0, v146
	v_cmp_neq_f32_e32 vcc, s35, v146
	s_nop 1
	v_cndmask_b32_e32 v150, 0, v146, vcc
	v_sub_f32_e32 v0, v191, v150
	v_mul_f32_e32 v0, 0x3fb8aa3b, v0
	v_exp_f32_e32 v0, v0
	s_nop 0
	v_cmp_neq_f32_e32 vcc, 1.0, v0
	s_cbranch_vccz .LBB0_806
	v_pk_mul_f32 v[64:65], v[64:65], v[0:1] op_sel_hi:[1,0]
	v_pk_mul_f32 v[62:63], v[62:63], v[0:1] op_sel_hi:[1,0]
	v_pk_mul_f32 v[60:61], v[60:61], v[0:1] op_sel_hi:[1,0]
	v_pk_mul_f32 v[58:59], v[58:59], v[0:1] op_sel_hi:[1,0]
	v_pk_mul_f32 v[56:57], v[56:57], v[0:1] op_sel_hi:[1,0]
	v_pk_mul_f32 v[54:55], v[54:55], v[0:1] op_sel_hi:[1,0]
	v_pk_mul_f32 v[52:53], v[52:53], v[0:1] op_sel_hi:[1,0]
	v_pk_mul_f32 v[50:51], v[50:51], v[0:1] op_sel_hi:[1,0]
	v_pk_mul_f32 v[48:49], v[48:49], v[0:1] op_sel_hi:[1,0]
	v_pk_mul_f32 v[46:47], v[46:47], v[0:1] op_sel_hi:[1,0]
	v_pk_mul_f32 v[44:45], v[44:45], v[0:1] op_sel_hi:[1,0]
	v_pk_mul_f32 v[42:43], v[42:43], v[0:1] op_sel_hi:[1,0]
	v_pk_mul_f32 v[40:41], v[40:41], v[0:1] op_sel_hi:[1,0]
	v_pk_mul_f32 v[38:39], v[38:39], v[0:1] op_sel_hi:[1,0]
	v_pk_mul_f32 v[36:37], v[36:37], v[0:1] op_sel_hi:[1,0]
	v_pk_mul_f32 v[34:35], v[34:35], v[0:1] op_sel_hi:[1,0]
